# same as the out-of-line version with one 8-byte scalar pad before block 1's softmax (code placement)
# speedup vs baseline: 1.0118x; 1.0118x over previous
; __device__ __forceinline__ void partialSM(f32x16& p0, f32x16& p1, float& m_reg, float& mn, float& alpha) {
;     constexpr float Cc = SCALE * 1.4426950408889634f;
;     float pmax = p0[0];
; #pragma unroll
;     for (int r = 1; r < 16; ++r) pmax = fmaxf(pmax, p0[r]);
; #pragma unroll
;     for (int r = 0; r < 16; ++r) pmax = fmaxf(pmax, p1[r]);
;     { auto rr = __builtin_amdgcn_permlane32_swap(__float_as_uint(pmax), __float_as_uint(pmax), false, false);
;       pmax = fmaxf(__uint_as_float(rr[0]), __uint_as_float(rr[1])); }
;     if (__builtin_expect(__all(pmax - m_reg <= THR / SCALE), 1)) { mn = m_reg; alpha = 1.f; }
;     else { mn = fmaxf(m_reg, pmax); alpha = __builtin_amdgcn_exp2f((m_reg - mn) * Cc); m_reg = mn; }
;     const float mnC = -mn * Cc;
;     { typedef float f32x2 __attribute__((ext_vector_type(2))); const f32x2 c2 = {Cc, Cc}, m2 = {mnC, mnC};
; #pragma unroll
;       for (int r = 0; r < 16; r += 2) { f32x2 t = {p0[r], p0[r + 1]}; t = __builtin_elementwise_fma(t, c2, m2); p0[r] = t.x; p0[r + 1] = t.y; }
; #pragma unroll
;       for (int r = 0; r < 16; r += 2) { f32x2 t = {p1[r], p1[r + 1]}; t = __builtin_elementwise_fma(t, c2, m2); p1[r] = t.x; p1[r + 1] = t.y; } }
; #pragma unroll
;     for (int r = 0; r < 16; ++r) p0[r] = __builtin_amdgcn_exp2f(p0[r]);
; }
; __device__ __forceinline__ void finishSM(f32x16& p0, f32x16& p1, float alpha, float& l_reg, bf16x8& pa0, bf16x8& pa1, bf16x8& pa2, bf16x8& pa3) {
; #pragma unroll
;     for (int r = 0; r < 16; ++r) p1[r] = __builtin_amdgcn_exp2f(p1[r]);
;     float ps;
;     { typedef float f32x2 __attribute__((ext_vector_type(2))); f32x2 s0 = {p0[0], p0[1]}, s1 = {p1[0], p1[1]};
; #pragma unroll
;       for (int r = 2; r < 16; r += 2) { s0 += (f32x2){p0[r], p0[r + 1]}; s1 += (f32x2){p1[r], p1[r + 1]}; }
;       s0 += s1; ps = s0.x + s0.y; }
;     { auto rr = __builtin_amdgcn_permlane32_swap(__float_as_uint(ps), __float_as_uint(ps), false, false);
;       ps = __uint_as_float(rr[0]) + __uint_as_float(rr[1]); }
;     l_reg = l_reg * alpha + ps;
;     ...
;     PK4(p0, 0, pa0); PK4(p0, 8, pa1); PK4(p1, 0, pa2); PK4(p1, 8, pa3);
.LA_g1b:
	ds_read_b64_tr_b16 v[74:75], v202 offset:0
	ds_read_b64_tr_b16 v[76:77], v202 offset:2048
	ds_read_b64_tr_b16 v[78:79], v202 offset:4096
	ds_read_b64_tr_b16 v[80:81], v202 offset:6144
	ds_read_b64_tr_b16 v[90:91], v202 offset:8192
	ds_read_b64_tr_b16 v[92:93], v202 offset:10240
	ds_read_b64_tr_b16 v[94:95], v202 offset:12288
	ds_read_b64_tr_b16 v[96:97], v202 offset:14336
	s_mov_b32 s47, 0x12345678
	v_max_f32_e32 v212, v98, v99
	v_max_f32_e32 v213, v114, v115
	v_max3_f32 v212, v212, v100, v101
	v_max3_f32 v213, v213, v116, v117
	v_max3_f32 v212, v212, v102, v103
	v_max3_f32 v213, v213, v118, v119
	v_max3_f32 v212, v212, v104, v105
	v_max3_f32 v213, v213, v120, v121
	v_max3_f32 v212, v212, v106, v107
	v_max3_f32 v213, v213, v122, v123
	v_max3_f32 v212, v212, v108, v109
	v_max3_f32 v213, v213, v124, v125
	v_max3_f32 v212, v212, v110, v111
	v_max3_f32 v213, v213, v126, v127
	v_max3_f32 v212, v212, v112, v113
	v_max3_f32 v213, v213, v128, v129
	v_max_f32_e32 v212, v212, v213
	v_mov_b32_e32 v213, v212
	s_nop 1
	v_permlane32_swap_b32_e32 v212, v213
	v_max_f32_e32 v212, v212, v213
	v_sub_f32_e32 v214, v212, v139
	v_cmp_ge_f32_e32 vcc, s67, v214
	v_max_f32_e32 v212, v139, v212
	v_sub_f32_e64 v214, v139, v212
	v_mul_f32_e32 v214, 0x3e16c740, v214
	v_exp_f32_e64 v215, v214
	s_cmp_eq_u64 vcc, exec
	s_cselect_b64 s[58:59], -1, 0
	v_cndmask_b32_e64 v139, v212, v139, s[58:59]
	v_cndmask_b32_e64 v215, v215, 1.0, s[58:59]
	v_mul_f32_e32 v216, 0xbe16c740, v139
	v_fma_f32 v98, v98, s52, v216
	v_fma_f32 v99, v99, s52, v216
	v_fma_f32 v100, v100, s52, v216
	v_fma_f32 v101, v101, s52, v216
	v_fma_f32 v102, v102, s52, v216
	v_fma_f32 v103, v103, s52, v216
	v_fma_f32 v104, v104, s52, v216
	v_fma_f32 v105, v105, s52, v216
	v_fma_f32 v106, v106, s52, v216
	v_fma_f32 v107, v107, s52, v216
	v_fma_f32 v108, v108, s52, v216
	v_fma_f32 v109, v109, s52, v216
	v_fma_f32 v110, v110, s52, v216
	v_fma_f32 v111, v111, s52, v216
	v_fma_f32 v112, v112, s52, v216
	v_fma_f32 v113, v113, s52, v216
	v_fma_f32 v114, v114, s52, v216
	v_fma_f32 v115, v115, s52, v216
	v_fma_f32 v116, v116, s52, v216
	v_fma_f32 v117, v117, s52, v216
	v_fma_f32 v118, v118, s52, v216
	v_fma_f32 v119, v119, s52, v216
	v_fma_f32 v120, v120, s52, v216
	v_fma_f32 v121, v121, s52, v216
	v_fma_f32 v122, v122, s52, v216
	v_fma_f32 v123, v123, s52, v216
	v_fma_f32 v124, v124, s52, v216
	v_fma_f32 v125, v125, s52, v216
	v_fma_f32 v126, v126, s52, v216
	v_fma_f32 v127, v127, s52, v216
	v_fma_f32 v128, v128, s52, v216
	v_fma_f32 v129, v129, s52, v216
	v_exp_f32_e32 v98, v98
	v_exp_f32_e32 v99, v99
	v_exp_f32_e32 v100, v100
	v_exp_f32_e32 v101, v101
	v_exp_f32_e32 v102, v102
	v_exp_f32_e32 v103, v103
	v_exp_f32_e32 v104, v104
	v_exp_f32_e32 v105, v105
	v_exp_f32_e32 v106, v106
	v_exp_f32_e32 v107, v107
	v_exp_f32_e32 v108, v108
	v_exp_f32_e32 v109, v109
	v_exp_f32_e32 v110, v110
	v_exp_f32_e32 v111, v111
	v_exp_f32_e32 v112, v112
	v_exp_f32_e32 v113, v113
	v_exp_f32_e32 v114, v114
	v_exp_f32_e32 v115, v115
	v_exp_f32_e32 v116, v116
	v_exp_f32_e32 v117, v117
	v_exp_f32_e32 v118, v118
	v_exp_f32_e32 v119, v119
	v_exp_f32_e32 v120, v120
	v_exp_f32_e32 v121, v121
	v_exp_f32_e32 v122, v122
	v_exp_f32_e32 v123, v123
	v_exp_f32_e32 v124, v124
	v_exp_f32_e32 v125, v125
	v_exp_f32_e32 v126, v126
	v_exp_f32_e32 v127, v127
	v_exp_f32_e32 v128, v128
	v_exp_f32_e32 v129, v129
	v_add_f32_e32 v212, v98, v100
	v_add_f32_e32 v213, v99, v101
	v_add_f32_e32 v212, v102, v212
	v_add_f32_e32 v213, v103, v213
	v_add_f32_e32 v212, v104, v212
	v_add_f32_e32 v213, v105, v213
	v_add_f32_e32 v212, v106, v212
	v_add_f32_e32 v213, v107, v213
	v_add_f32_e32 v212, v108, v212
	v_add_f32_e32 v213, v109, v213
	v_add_f32_e32 v212, v110, v212
	v_add_f32_e32 v213, v111, v213
	v_add_f32_e32 v212, v112, v212
	v_add_f32_e32 v213, v113, v213
	v_add_f32_e32 v212, v114, v212
	v_add_f32_e32 v213, v115, v213
	v_add_f32_e32 v212, v116, v212
	v_add_f32_e32 v213, v117, v213
	v_add_f32_e32 v212, v118, v212
	v_add_f32_e32 v213, v119, v213
	v_add_f32_e32 v212, v120, v212
	v_add_f32_e32 v213, v121, v213
	v_add_f32_e32 v212, v122, v212
	v_add_f32_e32 v213, v123, v213
	v_add_f32_e32 v212, v124, v212
	v_add_f32_e32 v213, v125, v213
	v_add_f32_e32 v212, v126, v212
	v_add_f32_e32 v213, v127, v213
	v_add_f32_e32 v212, v128, v212
	v_add_f32_e32 v213, v129, v213
	v_add_f32_e64 v212, v212, v213
	v_fma_f32 v255, v255, v215, v212
	v_cvt_pk_bf16_f32 v98, v98, v99
	v_cvt_pk_bf16_f32 v99, v100, v101
	v_cvt_pk_bf16_f32 v100, v102, v103
	v_cvt_pk_bf16_f32 v101, v104, v105
	v_cvt_pk_bf16_f32 v102, v106, v107
	v_cvt_pk_bf16_f32 v103, v108, v109
	v_cvt_pk_bf16_f32 v104, v110, v111
	v_cvt_pk_bf16_f32 v105, v112, v113
	v_cvt_pk_bf16_f32 v114, v114, v115
	v_cvt_pk_bf16_f32 v115, v116, v117
	v_cvt_pk_bf16_f32 v116, v118, v119
	v_cvt_pk_bf16_f32 v117, v120, v121
	v_cvt_pk_bf16_f32 v118, v122, v123
	v_cvt_pk_bf16_f32 v119, v124, v125
	v_cvt_pk_bf16_f32 v120, v126, v127
	v_cvt_pk_bf16_f32 v121, v128, v129
	v_permlane32_swap_b32_e32 v98, v100
	v_permlane32_swap_b32_e32 v99, v101
	v_permlane32_swap_b32_e32 v102, v104
	v_permlane32_swap_b32_e32 v103, v105
	v_permlane32_swap_b32_e32 v114, v116
	v_permlane32_swap_b32_e32 v115, v117
	v_permlane32_swap_b32_e32 v118, v120
	v_permlane32_swap_b32_e32 v119, v121
	v_cmp_gt_f32_e32 vcc, 1.0, v215
	s_cbranch_vccnz .LA_slow1
